# speedup vs baseline: 1.0134x; 1.0024x over previous
; __global__ void __launch_bounds__(512, 2) fwd_megakernel(Args a) {
;     ...
;             for (int tile = blk; tile < M / 32; tile += G) {
;                 const int m0 = tile * 32;
;                 f32x4 acc2[2];
; #pragma unroll
;                 for (int mt = 0; mt < 2; ++mt) acc2[mt] = (f32x4){0.f, 0.f, 0.f, 0.f};
;                 const u16* bp = WX + (size_t)(16 * wave + lq) * DM + 8 * lg;
;                 const u16* ap0 = XN + (size_t)(m0 + lq) * DM + 8 * lg; const u16* ap1 = ap0 + (size_t)16 * DM;
; #pragma unroll 16
;                 for (int ks = 0; ks < DM / 32; ++ks) {
;                     const bf16x8 bv = *(const bf16x8*)(bp + 32 * ks);
;                     const bf16x8 av0 = *(const bf16x8*)(ap0 + 32 * ks), av1 = *(const bf16x8*)(ap1 + 32 * ks);
;                     acc2[0] = __builtin_amdgcn_mfma_f32_16x16x32_bf16(av0, bv, acc2[0], 0, 0, 0);
;                     acc2[1] = __builtin_amdgcn_mfma_f32_16x16x32_bf16(av1, bv, acc2[1], 0, 0, 0);
;                 }
; #pragma unroll
;                 for (int mt = 0; mt < 2; ++mt)
; #pragma unroll
;                     for (int j = 0; j < 4; ++j) XWXA[(size_t)(m0 + 16 * mt + 4 * lg + j) * 128 + 16 * wave + lq] = acc2[mt][j];
.LBB0_133:
	s_add_u32 s0, s88, 0xab00000
	s_addc_u32 s1, s89, 0
	v_lshrrev_b32_e32 v202, 4, v225
	s_cmpk_lt_i32 s97, 0x100
	s_cselect_b64 s[4:5], -1, 0
	s_cmpk_gt_i32 s97, 0xff
	v_lshlrev_b32_e32 v201, 2, v202
	v_lshlrev_b32_e32 v164, 2, v162
	v_and_b32_e32 v138, 48, v218
	s_cbranch_scc1 .LBB0_138
	v_mov_b32_e32 v165, 0
	v_mov_b32_e32 v139, 0
	v_readlane_b32 s6, v252, 14
	v_readlane_b32 s14, v252, 6
	v_readlane_b32 s15, v252, 7
	v_lshl_or_b32 v226, v162, 12, v138
	v_add_u32_e32 v229, 0x10000, v226
	v_lshl_add_u32 v227, v201, 9, v164
	v_add_u32_e32 v228, 0x2000, v227
	s_lshl_b32 s2, s6, 16
	s_add_u32 s8, s88, 0xff80000
	s_addc_u32 s9, s89, 0
	s_add_u32 s8, s8, s2
	s_addc_u32 s9, s9, 0
	s_lshl_b32 s2, s6, 6
	s_add_u32 s10, s0, s2
	s_addc_u32 s11, s1, 0
	s_mov_b32 s3, s97
.Lxw_tile:
	s_lshl_b32 s2, s3, 17
	s_add_u32 s6, s14, s2
	s_addc_u32 s7, s15, 0
	s_lshl_b32 s2, s3, 14
	s_add_u32 s12, s10, s2
	s_addc_u32 s13, s11, 0
	v_mov_b32_e32 v208, 0
	v_mov_b32_e32 v209, 0
	v_mov_b32_e32 v210, 0
	v_mov_b32_e32 v211, 0
	v_mov_b32_e32 v212, 0
	v_mov_b32_e32 v213, 0
	v_mov_b32_e32 v214, 0
	v_mov_b32_e32 v215, 0
	global_load_dwordx4 v[0:3], v226, s[6:7]
	global_load_dwordx4 v[4:7], v229, s[6:7]
	global_load_dwordx4 v[8:11], v226, s[8:9]
	global_load_dwordx4 v[12:15], v226, s[6:7] offset:64
	global_load_dwordx4 v[16:19], v229, s[6:7] offset:64
	global_load_dwordx4 v[20:23], v226, s[8:9] offset:64
	global_load_dwordx4 v[24:27], v226, s[6:7] offset:128
	global_load_dwordx4 v[28:31], v229, s[6:7] offset:128
	global_load_dwordx4 v[32:35], v226, s[8:9] offset:128
	global_load_dwordx4 v[36:39], v226, s[6:7] offset:192
	global_load_dwordx4 v[40:43], v229, s[6:7] offset:192
	global_load_dwordx4 v[44:47], v226, s[8:9] offset:192
	global_load_dwordx4 v[48:51], v226, s[6:7] offset:256
	global_load_dwordx4 v[52:55], v229, s[6:7] offset:256
	global_load_dwordx4 v[56:59], v226, s[8:9] offset:256
	global_load_dwordx4 v[60:63], v226, s[6:7] offset:320
	global_load_dwordx4 v[64:67], v229, s[6:7] offset:320
	global_load_dwordx4 v[68:71], v226, s[8:9] offset:320
	global_load_dwordx4 v[72:75], v226, s[6:7] offset:384
	global_load_dwordx4 v[76:79], v229, s[6:7] offset:384
	global_load_dwordx4 v[80:83], v226, s[8:9] offset:384
	global_load_dwordx4 v[84:87], v226, s[6:7] offset:448
	global_load_dwordx4 v[88:91], v229, s[6:7] offset:448
	global_load_dwordx4 v[92:95], v226, s[8:9] offset:448
	global_load_dwordx4 v[96:99], v226, s[6:7] offset:512
	global_load_dwordx4 v[100:103], v229, s[6:7] offset:512
	global_load_dwordx4 v[104:107], v226, s[8:9] offset:512
	global_load_dwordx4 v[108:111], v226, s[6:7] offset:576
	global_load_dwordx4 v[112:115], v229, s[6:7] offset:576
	global_load_dwordx4 v[116:119], v226, s[8:9] offset:576
	global_load_dwordx4 v[120:123], v226, s[6:7] offset:640
	global_load_dwordx4 v[124:127], v229, s[6:7] offset:640
	global_load_dwordx4 v[142:145], v226, s[8:9] offset:640
	global_load_dwordx4 v[146:149], v226, s[6:7] offset:704
	global_load_dwordx4 v[172:175], v229, s[6:7] offset:704
	global_load_dwordx4 v[176:179], v226, s[8:9] offset:704
	global_load_dwordx4 v[180:183], v226, s[6:7] offset:768
	global_load_dwordx4 v[184:187], v229, s[6:7] offset:768
	global_load_dwordx4 v[188:191], v226, s[8:9] offset:768
	global_load_dwordx4 v[192:195], v226, s[6:7] offset:832
	global_load_dwordx4 v[196:199], v229, s[6:7] offset:832
	global_load_dwordx4 v[204:207], v226, s[8:9] offset:832
	s_waitcnt vmcnt(39)
	v_mfma_f32_16x16x32_bf16 v[208:211], v[0:3], v[8:11], v[208:211]
	v_mfma_f32_16x16x32_bf16 v[212:215], v[4:7], v[8:11], v[212:215]
	global_load_dwordx4 v[0:3], v226, s[6:7] offset:896
	global_load_dwordx4 v[4:7], v229, s[6:7] offset:896
	global_load_dwordx4 v[8:11], v226, s[8:9] offset:896
	s_waitcnt vmcnt(39)
	v_mfma_f32_16x16x32_bf16 v[208:211], v[12:15], v[20:23], v[208:211]
	v_mfma_f32_16x16x32_bf16 v[212:215], v[16:19], v[20:23], v[212:215]
	global_load_dwordx4 v[12:15], v226, s[6:7] offset:960
	global_load_dwordx4 v[16:19], v229, s[6:7] offset:960
	global_load_dwordx4 v[20:23], v226, s[8:9] offset:960
	s_waitcnt vmcnt(39)
	v_mfma_f32_16x16x32_bf16 v[208:211], v[24:27], v[32:35], v[208:211]
	v_mfma_f32_16x16x32_bf16 v[212:215], v[28:31], v[32:35], v[212:215]
	global_load_dwordx4 v[24:27], v226, s[6:7] offset:1024
	global_load_dwordx4 v[28:31], v229, s[6:7] offset:1024
	global_load_dwordx4 v[32:35], v226, s[8:9] offset:1024
	s_waitcnt vmcnt(39)
	v_mfma_f32_16x16x32_bf16 v[208:211], v[36:39], v[44:47], v[208:211]
	v_mfma_f32_16x16x32_bf16 v[212:215], v[40:43], v[44:47], v[212:215]
	global_load_dwordx4 v[36:39], v226, s[6:7] offset:1088
	global_load_dwordx4 v[40:43], v229, s[6:7] offset:1088
	global_load_dwordx4 v[44:47], v226, s[8:9] offset:1088
	s_waitcnt vmcnt(39)
	v_mfma_f32_16x16x32_bf16 v[208:211], v[48:51], v[56:59], v[208:211]
	v_mfma_f32_16x16x32_bf16 v[212:215], v[52:55], v[56:59], v[212:215]
	global_load_dwordx4 v[48:51], v226, s[6:7] offset:1152
	global_load_dwordx4 v[52:55], v229, s[6:7] offset:1152
	global_load_dwordx4 v[56:59], v226, s[8:9] offset:1152
	s_waitcnt vmcnt(39)
	v_mfma_f32_16x16x32_bf16 v[208:211], v[60:63], v[68:71], v[208:211]
	v_mfma_f32_16x16x32_bf16 v[212:215], v[64:67], v[68:71], v[212:215]
	global_load_dwordx4 v[60:63], v226, s[6:7] offset:1216
	global_load_dwordx4 v[64:67], v229, s[6:7] offset:1216
	global_load_dwordx4 v[68:71], v226, s[8:9] offset:1216
	s_waitcnt vmcnt(39)
	v_mfma_f32_16x16x32_bf16 v[208:211], v[72:75], v[80:83], v[208:211]
	v_mfma_f32_16x16x32_bf16 v[212:215], v[76:79], v[80:83], v[212:215]
	global_load_dwordx4 v[72:75], v226, s[6:7] offset:1280
	global_load_dwordx4 v[76:79], v229, s[6:7] offset:1280
	global_load_dwordx4 v[80:83], v226, s[8:9] offset:1280
	s_waitcnt vmcnt(39)
; __global__ void __launch_bounds__(512, 2) fwd_megakernel(Args a) {
;     ...
;                 for (int ks = 0; ks < DM / 32; ++ks) {
;                     const bf16x8 bv = *(const bf16x8*)(bp + 32 * ks);
;                     const bf16x8 av0 = *(const bf16x8*)(ap0 + 32 * ks), av1 = *(const bf16x8*)(ap1 + 32 * ks);
;                     acc2[0] = __builtin_amdgcn_mfma_f32_16x16x32_bf16(av0, bv, acc2[0], 0, 0, 0);
;                     acc2[1] = __builtin_amdgcn_mfma_f32_16x16x32_bf16(av1, bv, acc2[1], 0, 0, 0);
;                 }
	v_mfma_f32_16x16x32_bf16 v[208:211], v[84:87], v[92:95], v[208:211]
	v_mfma_f32_16x16x32_bf16 v[212:215], v[88:91], v[92:95], v[212:215]
	global_load_dwordx4 v[84:87], v226, s[6:7] offset:1344
	global_load_dwordx4 v[88:91], v229, s[6:7] offset:1344
	global_load_dwordx4 v[92:95], v226, s[8:9] offset:1344
	s_waitcnt vmcnt(39)
	v_mfma_f32_16x16x32_bf16 v[208:211], v[96:99], v[104:107], v[208:211]
	v_mfma_f32_16x16x32_bf16 v[212:215], v[100:103], v[104:107], v[212:215]
	global_load_dwordx4 v[96:99], v226, s[6:7] offset:1408
	global_load_dwordx4 v[100:103], v229, s[6:7] offset:1408
	global_load_dwordx4 v[104:107], v226, s[8:9] offset:1408
	s_waitcnt vmcnt(39)
	v_mfma_f32_16x16x32_bf16 v[208:211], v[108:111], v[116:119], v[208:211]
	v_mfma_f32_16x16x32_bf16 v[212:215], v[112:115], v[116:119], v[212:215]
	global_load_dwordx4 v[108:111], v226, s[6:7] offset:1472
	global_load_dwordx4 v[112:115], v229, s[6:7] offset:1472
	global_load_dwordx4 v[116:119], v226, s[8:9] offset:1472
	s_waitcnt vmcnt(39)
	v_mfma_f32_16x16x32_bf16 v[208:211], v[120:123], v[142:145], v[208:211]
	v_mfma_f32_16x16x32_bf16 v[212:215], v[124:127], v[142:145], v[212:215]
	global_load_dwordx4 v[120:123], v226, s[6:7] offset:1536
	global_load_dwordx4 v[124:127], v229, s[6:7] offset:1536
	global_load_dwordx4 v[142:145], v226, s[8:9] offset:1536
	s_waitcnt vmcnt(39)
	v_mfma_f32_16x16x32_bf16 v[208:211], v[146:149], v[176:179], v[208:211]
	v_mfma_f32_16x16x32_bf16 v[212:215], v[172:175], v[176:179], v[212:215]
	global_load_dwordx4 v[146:149], v226, s[6:7] offset:1600
	global_load_dwordx4 v[172:175], v229, s[6:7] offset:1600
	global_load_dwordx4 v[176:179], v226, s[8:9] offset:1600
	s_waitcnt vmcnt(39)
	v_mfma_f32_16x16x32_bf16 v[208:211], v[180:183], v[188:191], v[208:211]
	v_mfma_f32_16x16x32_bf16 v[212:215], v[184:187], v[188:191], v[212:215]
	global_load_dwordx4 v[180:183], v226, s[6:7] offset:1664
	global_load_dwordx4 v[184:187], v229, s[6:7] offset:1664
	global_load_dwordx4 v[188:191], v226, s[8:9] offset:1664
	s_waitcnt vmcnt(39)
	v_mfma_f32_16x16x32_bf16 v[208:211], v[192:195], v[204:207], v[208:211]
	v_mfma_f32_16x16x32_bf16 v[212:215], v[196:199], v[204:207], v[212:215]
	global_load_dwordx4 v[192:195], v226, s[6:7] offset:1728
	global_load_dwordx4 v[196:199], v229, s[6:7] offset:1728
	global_load_dwordx4 v[204:207], v226, s[8:9] offset:1728
	s_waitcnt vmcnt(39)
	v_mfma_f32_16x16x32_bf16 v[208:211], v[0:3], v[8:11], v[208:211]
	v_mfma_f32_16x16x32_bf16 v[212:215], v[4:7], v[8:11], v[212:215]
	global_load_dwordx4 v[0:3], v226, s[6:7] offset:1792
	global_load_dwordx4 v[4:7], v229, s[6:7] offset:1792
	global_load_dwordx4 v[8:11], v226, s[8:9] offset:1792
	s_waitcnt vmcnt(39)
	v_mfma_f32_16x16x32_bf16 v[208:211], v[12:15], v[20:23], v[208:211]
	v_mfma_f32_16x16x32_bf16 v[212:215], v[16:19], v[20:23], v[212:215]
	global_load_dwordx4 v[12:15], v226, s[6:7] offset:1856
	global_load_dwordx4 v[16:19], v229, s[6:7] offset:1856
	global_load_dwordx4 v[20:23], v226, s[8:9] offset:1856
	s_waitcnt vmcnt(39)
	v_mfma_f32_16x16x32_bf16 v[208:211], v[24:27], v[32:35], v[208:211]
	v_mfma_f32_16x16x32_bf16 v[212:215], v[28:31], v[32:35], v[212:215]
	global_load_dwordx4 v[24:27], v226, s[6:7] offset:1920
	global_load_dwordx4 v[28:31], v229, s[6:7] offset:1920
	global_load_dwordx4 v[32:35], v226, s[8:9] offset:1920
	s_waitcnt vmcnt(39)
	v_mfma_f32_16x16x32_bf16 v[208:211], v[36:39], v[44:47], v[208:211]
	v_mfma_f32_16x16x32_bf16 v[212:215], v[40:43], v[44:47], v[212:215]
	global_load_dwordx4 v[36:39], v226, s[6:7] offset:1984
	global_load_dwordx4 v[40:43], v229, s[6:7] offset:1984
	global_load_dwordx4 v[44:47], v226, s[8:9] offset:1984
	s_waitcnt vmcnt(39)
	v_mfma_f32_16x16x32_bf16 v[208:211], v[48:51], v[56:59], v[208:211]
	v_mfma_f32_16x16x32_bf16 v[212:215], v[52:55], v[56:59], v[212:215]
	global_load_dwordx4 v[48:51], v226, s[6:7] offset:2048
	global_load_dwordx4 v[52:55], v229, s[6:7] offset:2048
	global_load_dwordx4 v[56:59], v226, s[8:9] offset:2048
	s_waitcnt vmcnt(39)
	v_mfma_f32_16x16x32_bf16 v[208:211], v[60:63], v[68:71], v[208:211]
	v_mfma_f32_16x16x32_bf16 v[212:215], v[64:67], v[68:71], v[212:215]
	global_load_dwordx4 v[60:63], v226, s[6:7] offset:2112
	global_load_dwordx4 v[64:67], v229, s[6:7] offset:2112
	global_load_dwordx4 v[68:71], v226, s[8:9] offset:2112
	s_waitcnt vmcnt(39)
	v_mfma_f32_16x16x32_bf16 v[208:211], v[72:75], v[80:83], v[208:211]
	v_mfma_f32_16x16x32_bf16 v[212:215], v[76:79], v[80:83], v[212:215]
	global_load_dwordx4 v[72:75], v226, s[6:7] offset:2176
	global_load_dwordx4 v[76:79], v229, s[6:7] offset:2176
	global_load_dwordx4 v[80:83], v226, s[8:9] offset:2176
	s_waitcnt vmcnt(39)
	v_mfma_f32_16x16x32_bf16 v[208:211], v[84:87], v[92:95], v[208:211]
	v_mfma_f32_16x16x32_bf16 v[212:215], v[88:91], v[92:95], v[212:215]
	global_load_dwordx4 v[84:87], v226, s[6:7] offset:2240
	global_load_dwordx4 v[88:91], v229, s[6:7] offset:2240
	global_load_dwordx4 v[92:95], v226, s[8:9] offset:2240
	s_waitcnt vmcnt(39)
	v_mfma_f32_16x16x32_bf16 v[208:211], v[96:99], v[104:107], v[208:211]
	v_mfma_f32_16x16x32_bf16 v[212:215], v[100:103], v[104:107], v[212:215]
	global_load_dwordx4 v[96:99], v226, s[6:7] offset:2304
	global_load_dwordx4 v[100:103], v229, s[6:7] offset:2304
	global_load_dwordx4 v[104:107], v226, s[8:9] offset:2304
	s_waitcnt vmcnt(39)
	v_mfma_f32_16x16x32_bf16 v[208:211], v[108:111], v[116:119], v[208:211]
	v_mfma_f32_16x16x32_bf16 v[212:215], v[112:115], v[116:119], v[212:215]
	global_load_dwordx4 v[108:111], v226, s[6:7] offset:2368
	global_load_dwordx4 v[112:115], v229, s[6:7] offset:2368
	global_load_dwordx4 v[116:119], v226, s[8:9] offset:2368
	s_waitcnt vmcnt(39)
; __global__ void __launch_bounds__(512, 2) fwd_megakernel(Args a) {
;     ...
;                 for (int ks = 0; ks < DM / 32; ++ks) {
;                     const bf16x8 bv = *(const bf16x8*)(bp + 32 * ks);
;                     const bf16x8 av0 = *(const bf16x8*)(ap0 + 32 * ks), av1 = *(const bf16x8*)(ap1 + 32 * ks);
;                     acc2[0] = __builtin_amdgcn_mfma_f32_16x16x32_bf16(av0, bv, acc2[0], 0, 0, 0);
;                     acc2[1] = __builtin_amdgcn_mfma_f32_16x16x32_bf16(av1, bv, acc2[1], 0, 0, 0);
;                 }
	v_mfma_f32_16x16x32_bf16 v[208:211], v[120:123], v[142:145], v[208:211]
	v_mfma_f32_16x16x32_bf16 v[212:215], v[124:127], v[142:145], v[212:215]
	global_load_dwordx4 v[120:123], v226, s[6:7] offset:2432
	global_load_dwordx4 v[124:127], v229, s[6:7] offset:2432
	global_load_dwordx4 v[142:145], v226, s[8:9] offset:2432
	s_waitcnt vmcnt(39)
	v_mfma_f32_16x16x32_bf16 v[208:211], v[146:149], v[176:179], v[208:211]
	v_mfma_f32_16x16x32_bf16 v[212:215], v[172:175], v[176:179], v[212:215]
	global_load_dwordx4 v[146:149], v226, s[6:7] offset:2496
	global_load_dwordx4 v[172:175], v229, s[6:7] offset:2496
	global_load_dwordx4 v[176:179], v226, s[8:9] offset:2496
	s_waitcnt vmcnt(39)
	v_mfma_f32_16x16x32_bf16 v[208:211], v[180:183], v[188:191], v[208:211]
	v_mfma_f32_16x16x32_bf16 v[212:215], v[184:187], v[188:191], v[212:215]
	global_load_dwordx4 v[180:183], v226, s[6:7] offset:2560
	global_load_dwordx4 v[184:187], v229, s[6:7] offset:2560
	global_load_dwordx4 v[188:191], v226, s[8:9] offset:2560
	s_waitcnt vmcnt(39)
	v_mfma_f32_16x16x32_bf16 v[208:211], v[192:195], v[204:207], v[208:211]
	v_mfma_f32_16x16x32_bf16 v[212:215], v[196:199], v[204:207], v[212:215]
	global_load_dwordx4 v[192:195], v226, s[6:7] offset:2624
	global_load_dwordx4 v[196:199], v229, s[6:7] offset:2624
	global_load_dwordx4 v[204:207], v226, s[8:9] offset:2624
	s_waitcnt vmcnt(39)
	v_mfma_f32_16x16x32_bf16 v[208:211], v[0:3], v[8:11], v[208:211]
	v_mfma_f32_16x16x32_bf16 v[212:215], v[4:7], v[8:11], v[212:215]
	global_load_dwordx4 v[0:3], v226, s[6:7] offset:2688
	global_load_dwordx4 v[4:7], v229, s[6:7] offset:2688
	global_load_dwordx4 v[8:11], v226, s[8:9] offset:2688
	s_waitcnt vmcnt(39)
	v_mfma_f32_16x16x32_bf16 v[208:211], v[12:15], v[20:23], v[208:211]
	v_mfma_f32_16x16x32_bf16 v[212:215], v[16:19], v[20:23], v[212:215]
	global_load_dwordx4 v[12:15], v226, s[6:7] offset:2752
	global_load_dwordx4 v[16:19], v229, s[6:7] offset:2752
	global_load_dwordx4 v[20:23], v226, s[8:9] offset:2752
	s_waitcnt vmcnt(39)
	v_mfma_f32_16x16x32_bf16 v[208:211], v[24:27], v[32:35], v[208:211]
	v_mfma_f32_16x16x32_bf16 v[212:215], v[28:31], v[32:35], v[212:215]
	global_load_dwordx4 v[24:27], v226, s[6:7] offset:2816
	global_load_dwordx4 v[28:31], v229, s[6:7] offset:2816
	global_load_dwordx4 v[32:35], v226, s[8:9] offset:2816
	s_waitcnt vmcnt(39)
	v_mfma_f32_16x16x32_bf16 v[208:211], v[36:39], v[44:47], v[208:211]
	v_mfma_f32_16x16x32_bf16 v[212:215], v[40:43], v[44:47], v[212:215]
	global_load_dwordx4 v[36:39], v226, s[6:7] offset:2880
	global_load_dwordx4 v[40:43], v229, s[6:7] offset:2880
	global_load_dwordx4 v[44:47], v226, s[8:9] offset:2880
	s_waitcnt vmcnt(39)
	v_mfma_f32_16x16x32_bf16 v[208:211], v[48:51], v[56:59], v[208:211]
	v_mfma_f32_16x16x32_bf16 v[212:215], v[52:55], v[56:59], v[212:215]
	global_load_dwordx4 v[48:51], v226, s[6:7] offset:2944
	global_load_dwordx4 v[52:55], v229, s[6:7] offset:2944
	global_load_dwordx4 v[56:59], v226, s[8:9] offset:2944
	s_waitcnt vmcnt(39)
	v_mfma_f32_16x16x32_bf16 v[208:211], v[60:63], v[68:71], v[208:211]
	v_mfma_f32_16x16x32_bf16 v[212:215], v[64:67], v[68:71], v[212:215]
	global_load_dwordx4 v[60:63], v226, s[6:7] offset:3008
	global_load_dwordx4 v[64:67], v229, s[6:7] offset:3008
	global_load_dwordx4 v[68:71], v226, s[8:9] offset:3008
	s_waitcnt vmcnt(39)
	v_mfma_f32_16x16x32_bf16 v[208:211], v[72:75], v[80:83], v[208:211]
	v_mfma_f32_16x16x32_bf16 v[212:215], v[76:79], v[80:83], v[212:215]
	global_load_dwordx4 v[72:75], v226, s[6:7] offset:3072
	global_load_dwordx4 v[76:79], v229, s[6:7] offset:3072
	global_load_dwordx4 v[80:83], v226, s[8:9] offset:3072
	s_waitcnt vmcnt(39)
	v_mfma_f32_16x16x32_bf16 v[208:211], v[84:87], v[92:95], v[208:211]
	v_mfma_f32_16x16x32_bf16 v[212:215], v[88:91], v[92:95], v[212:215]
	global_load_dwordx4 v[84:87], v226, s[6:7] offset:3136
	global_load_dwordx4 v[88:91], v229, s[6:7] offset:3136
	global_load_dwordx4 v[92:95], v226, s[8:9] offset:3136
	s_waitcnt vmcnt(39)
	v_mfma_f32_16x16x32_bf16 v[208:211], v[96:99], v[104:107], v[208:211]
	v_mfma_f32_16x16x32_bf16 v[212:215], v[100:103], v[104:107], v[212:215]
	global_load_dwordx4 v[96:99], v226, s[6:7] offset:3200
	global_load_dwordx4 v[100:103], v229, s[6:7] offset:3200
	global_load_dwordx4 v[104:107], v226, s[8:9] offset:3200
	s_waitcnt vmcnt(39)
	v_mfma_f32_16x16x32_bf16 v[208:211], v[108:111], v[116:119], v[208:211]
	v_mfma_f32_16x16x32_bf16 v[212:215], v[112:115], v[116:119], v[212:215]
	global_load_dwordx4 v[108:111], v226, s[6:7] offset:3264
	global_load_dwordx4 v[112:115], v229, s[6:7] offset:3264
	global_load_dwordx4 v[116:119], v226, s[8:9] offset:3264
	s_waitcnt vmcnt(39)
	v_mfma_f32_16x16x32_bf16 v[208:211], v[120:123], v[142:145], v[208:211]
	v_mfma_f32_16x16x32_bf16 v[212:215], v[124:127], v[142:145], v[212:215]
	global_load_dwordx4 v[120:123], v226, s[6:7] offset:3328
	global_load_dwordx4 v[124:127], v229, s[6:7] offset:3328
	global_load_dwordx4 v[142:145], v226, s[8:9] offset:3328
	s_waitcnt vmcnt(39)
	v_mfma_f32_16x16x32_bf16 v[208:211], v[146:149], v[176:179], v[208:211]
	v_mfma_f32_16x16x32_bf16 v[212:215], v[172:175], v[176:179], v[212:215]
	global_load_dwordx4 v[146:149], v226, s[6:7] offset:3392
	global_load_dwordx4 v[172:175], v229, s[6:7] offset:3392
	global_load_dwordx4 v[176:179], v226, s[8:9] offset:3392
	s_waitcnt vmcnt(39)
	v_mfma_f32_16x16x32_bf16 v[208:211], v[180:183], v[188:191], v[208:211]
	v_mfma_f32_16x16x32_bf16 v[212:215], v[184:187], v[188:191], v[212:215]
	global_load_dwordx4 v[180:183], v226, s[6:7] offset:3456
	global_load_dwordx4 v[184:187], v229, s[6:7] offset:3456
	global_load_dwordx4 v[188:191], v226, s[8:9] offset:3456
	s_waitcnt vmcnt(39)
; __global__ void __launch_bounds__(512, 2) fwd_megakernel(Args a) {
;     ...
;                 for (int ks = 0; ks < DM / 32; ++ks) {
;                     const bf16x8 bv = *(const bf16x8*)(bp + 32 * ks);
;                     const bf16x8 av0 = *(const bf16x8*)(ap0 + 32 * ks), av1 = *(const bf16x8*)(ap1 + 32 * ks);
;                     acc2[0] = __builtin_amdgcn_mfma_f32_16x16x32_bf16(av0, bv, acc2[0], 0, 0, 0);
;                     acc2[1] = __builtin_amdgcn_mfma_f32_16x16x32_bf16(av1, bv, acc2[1], 0, 0, 0);
;                 }
; #pragma unroll
;                 for (int mt = 0; mt < 2; ++mt)
; #pragma unroll
;                     for (int j = 0; j < 4; ++j) XWXA[(size_t)(m0 + 16 * mt + 4 * lg + j) * 128 + 16 * wave + lq] = acc2[mt][j];
	v_mfma_f32_16x16x32_bf16 v[208:211], v[192:195], v[204:207], v[208:211]
	v_mfma_f32_16x16x32_bf16 v[212:215], v[196:199], v[204:207], v[212:215]
	global_load_dwordx4 v[192:195], v226, s[6:7] offset:3520
	global_load_dwordx4 v[196:199], v229, s[6:7] offset:3520
	global_load_dwordx4 v[204:207], v226, s[8:9] offset:3520
	s_waitcnt vmcnt(39)
	v_mfma_f32_16x16x32_bf16 v[208:211], v[0:3], v[8:11], v[208:211]
	v_mfma_f32_16x16x32_bf16 v[212:215], v[4:7], v[8:11], v[212:215]
	global_load_dwordx4 v[0:3], v226, s[6:7] offset:3584
	global_load_dwordx4 v[4:7], v229, s[6:7] offset:3584
	global_load_dwordx4 v[8:11], v226, s[8:9] offset:3584
	s_waitcnt vmcnt(39)
	v_mfma_f32_16x16x32_bf16 v[208:211], v[12:15], v[20:23], v[208:211]
	v_mfma_f32_16x16x32_bf16 v[212:215], v[16:19], v[20:23], v[212:215]
	global_load_dwordx4 v[12:15], v226, s[6:7] offset:3648
	global_load_dwordx4 v[16:19], v229, s[6:7] offset:3648
	global_load_dwordx4 v[20:23], v226, s[8:9] offset:3648
	s_waitcnt vmcnt(39)
	v_mfma_f32_16x16x32_bf16 v[208:211], v[24:27], v[32:35], v[208:211]
	v_mfma_f32_16x16x32_bf16 v[212:215], v[28:31], v[32:35], v[212:215]
	global_load_dwordx4 v[24:27], v226, s[6:7] offset:3712
	global_load_dwordx4 v[28:31], v229, s[6:7] offset:3712
	global_load_dwordx4 v[32:35], v226, s[8:9] offset:3712
	s_waitcnt vmcnt(39)
	v_mfma_f32_16x16x32_bf16 v[208:211], v[36:39], v[44:47], v[208:211]
	v_mfma_f32_16x16x32_bf16 v[212:215], v[40:43], v[44:47], v[212:215]
	global_load_dwordx4 v[36:39], v226, s[6:7] offset:3776
	global_load_dwordx4 v[40:43], v229, s[6:7] offset:3776
	global_load_dwordx4 v[44:47], v226, s[8:9] offset:3776
	s_waitcnt vmcnt(39)
	v_mfma_f32_16x16x32_bf16 v[208:211], v[48:51], v[56:59], v[208:211]
	v_mfma_f32_16x16x32_bf16 v[212:215], v[52:55], v[56:59], v[212:215]
	global_load_dwordx4 v[48:51], v226, s[6:7] offset:3840
	global_load_dwordx4 v[52:55], v229, s[6:7] offset:3840
	global_load_dwordx4 v[56:59], v226, s[8:9] offset:3840
	s_waitcnt vmcnt(39)
	v_mfma_f32_16x16x32_bf16 v[208:211], v[60:63], v[68:71], v[208:211]
	v_mfma_f32_16x16x32_bf16 v[212:215], v[64:67], v[68:71], v[212:215]
	global_load_dwordx4 v[60:63], v226, s[6:7] offset:3904
	global_load_dwordx4 v[64:67], v229, s[6:7] offset:3904
	global_load_dwordx4 v[68:71], v226, s[8:9] offset:3904
	s_waitcnt vmcnt(39)
	v_mfma_f32_16x16x32_bf16 v[208:211], v[72:75], v[80:83], v[208:211]
	v_mfma_f32_16x16x32_bf16 v[212:215], v[76:79], v[80:83], v[212:215]
	global_load_dwordx4 v[72:75], v226, s[6:7] offset:3968
	global_load_dwordx4 v[76:79], v229, s[6:7] offset:3968
	global_load_dwordx4 v[80:83], v226, s[8:9] offset:3968
	s_waitcnt vmcnt(39)
	v_mfma_f32_16x16x32_bf16 v[208:211], v[84:87], v[92:95], v[208:211]
	v_mfma_f32_16x16x32_bf16 v[212:215], v[88:91], v[92:95], v[212:215]
	global_load_dwordx4 v[84:87], v226, s[6:7] offset:4032
	global_load_dwordx4 v[88:91], v229, s[6:7] offset:4032
	global_load_dwordx4 v[92:95], v226, s[8:9] offset:4032
	s_waitcnt vmcnt(39)
	v_mfma_f32_16x16x32_bf16 v[208:211], v[96:99], v[104:107], v[208:211]
	v_mfma_f32_16x16x32_bf16 v[212:215], v[100:103], v[104:107], v[212:215]
	s_waitcnt vmcnt(36)
	v_mfma_f32_16x16x32_bf16 v[208:211], v[108:111], v[116:119], v[208:211]
	v_mfma_f32_16x16x32_bf16 v[212:215], v[112:115], v[116:119], v[212:215]
	s_waitcnt vmcnt(33)
	v_mfma_f32_16x16x32_bf16 v[208:211], v[120:123], v[142:145], v[208:211]
	v_mfma_f32_16x16x32_bf16 v[212:215], v[124:127], v[142:145], v[212:215]
	s_waitcnt vmcnt(30)
	v_mfma_f32_16x16x32_bf16 v[208:211], v[146:149], v[176:179], v[208:211]
	v_mfma_f32_16x16x32_bf16 v[212:215], v[172:175], v[176:179], v[212:215]
	s_waitcnt vmcnt(27)
	v_mfma_f32_16x16x32_bf16 v[208:211], v[180:183], v[188:191], v[208:211]
	v_mfma_f32_16x16x32_bf16 v[212:215], v[184:187], v[188:191], v[212:215]
	s_waitcnt vmcnt(24)
	v_mfma_f32_16x16x32_bf16 v[208:211], v[192:195], v[204:207], v[208:211]
	v_mfma_f32_16x16x32_bf16 v[212:215], v[196:199], v[204:207], v[212:215]
	s_waitcnt vmcnt(21)
	v_mfma_f32_16x16x32_bf16 v[208:211], v[0:3], v[8:11], v[208:211]
	v_mfma_f32_16x16x32_bf16 v[212:215], v[4:7], v[8:11], v[212:215]
	s_waitcnt vmcnt(18)
	v_mfma_f32_16x16x32_bf16 v[208:211], v[12:15], v[20:23], v[208:211]
	v_mfma_f32_16x16x32_bf16 v[212:215], v[16:19], v[20:23], v[212:215]
	s_waitcnt vmcnt(15)
	v_mfma_f32_16x16x32_bf16 v[208:211], v[24:27], v[32:35], v[208:211]
	v_mfma_f32_16x16x32_bf16 v[212:215], v[28:31], v[32:35], v[212:215]
	s_waitcnt vmcnt(12)
	v_mfma_f32_16x16x32_bf16 v[208:211], v[36:39], v[44:47], v[208:211]
	v_mfma_f32_16x16x32_bf16 v[212:215], v[40:43], v[44:47], v[212:215]
	s_waitcnt vmcnt(9)
	v_mfma_f32_16x16x32_bf16 v[208:211], v[48:51], v[56:59], v[208:211]
	v_mfma_f32_16x16x32_bf16 v[212:215], v[52:55], v[56:59], v[212:215]
	s_waitcnt vmcnt(6)
	v_mfma_f32_16x16x32_bf16 v[208:211], v[60:63], v[68:71], v[208:211]
	v_mfma_f32_16x16x32_bf16 v[212:215], v[64:67], v[68:71], v[212:215]
	s_waitcnt vmcnt(3)
	v_mfma_f32_16x16x32_bf16 v[208:211], v[72:75], v[80:83], v[208:211]
	v_mfma_f32_16x16x32_bf16 v[212:215], v[76:79], v[80:83], v[212:215]
	s_waitcnt vmcnt(0)
	v_mfma_f32_16x16x32_bf16 v[208:211], v[84:87], v[92:95], v[208:211]
	v_mfma_f32_16x16x32_bf16 v[212:215], v[88:91], v[92:95], v[212:215]
	s_nop 7
	s_nop 1
	global_store_dword v227, v208, s[12:13]
	global_store_dword v227, v209, s[12:13] offset:512
	global_store_dword v227, v210, s[12:13] offset:1024
	global_store_dword v227, v211, s[12:13] offset:1536
	global_store_dword v228, v212, s[12:13]
	global_store_dword v228, v213, s[12:13] offset:512
	global_store_dword v228, v214, s[12:13] offset:1024
	global_store_dword v228, v215, s[12:13] offset:1536
	s_add_i32 s3, s3, s90
	s_cmpk_gt_i32 s3, 0xff
	s_cbranch_scc0 .Lxw_tile
